# O3c MFMA order + peeled first K-iteration in proj/pool/out GEMM loops (first-touch MFMAs use SrcC=0; 128 v_mov zero-inits per unit deleted); bit-identical
# speedup vs baseline: 1.0145x; 1.0007x over previous
; #define PG8_WAIT_L(n) asm volatile("s_waitcnt lgkmcnt(" #n ")" ::: "memory")
; #define PG8_BAR __builtin_amdgcn_s_barrier()
; #define PG8_SCHED __builtin_amdgcn_sched_barrier(0)
; template <class Epi, class AddrA, class AddrB>
; __device__ __forceinline__ void gemm_phase(const Sched S, const int lda, const int ldb, const int K, const AddrA addrA,
;                                            const AddrB addrB, const Epi E) {
;     ...
;     const bool has_next = S.next(ui + 1, nxt);
;     const char* nA = has_next ? addrA(nxt) : cA;
;     const char* nB = has_next ? addrB(nxt) : cB;
;     for (int t = 0; t < nt; t += 2) {
;       const bool last = (t == nt - 2);
;       const char* a1 = cA + (size_t)(t + 1) * kstep;
;       const char* a2 = last ? nA : cA + (size_t)(t + 2) * kstep;
;       const char* b2 = last ? nB : cB + (size_t)(t + 2) * kstep;
;       const char* a3 = a2 + kstep;
;       const char* b3 = b2 + kstep;
;       PG8_LDB(B0, 0, 0); PG8_SCHED; PG8_LDA(At, 0, 0); PG8_STAGE(PG8_SA(1, 1), a1 + hstepA, voffA);
;       PG8_WAIT_L(8); PG8_BAR; PG8_WAIT_L(0); PG8_MMA(0, 0, At, B0); PG8_BAR; PG8_SCHED;
;       PG8_LDB(B1, 0, 1); PG8_STAGE(PG8_SB(0, 0), b2, voffB);
;       PG8_BAR; PG8_WAIT_L(0); PG8_MMA(0, 1, At, B1); PG8_BAR;
;       PG8_LDA(At, 0, 1); PG8_STAGE(PG8_SA(0, 0), a2, voffA);
;       PG8_BAR; PG8_WAIT_L(0); PG8_MMA(1, 0, At, B0); PG8_BAR; PG8_SCHED;
.LBB0_108:
	s_ashr_i32 s1, s0, 31
	s_lshl_b64 s[6:7], s[0:1], 20
	s_add_u32 s6, s20, s6
	s_addc_u32 s7, s21, s7
	s_and_b64 s[8:9], s[16:17], exec
	s_cselect_b32 s1, s7, s15
	s_cselect_b32 s11, s6, s14
	s_ashr_i32 s3, s2, 31
	s_lshl_b64 s[8:9], s[2:3], 20
	s_add_u32 s8, s22, s8
	s_addc_u32 s9, s23, s9
	s_and_b64 s[16:17], s[16:17], exec
	s_cselect_b32 s3, s9, s13
	s_cselect_b32 s36, s8, s12
	s_add_u32 s37, s12, 0x100
	s_addc_u32 s38, s13, 0
	s_add_u32 s12, s14, 0x80080
	s_addc_u32 s13, s15, 0
	s_mov_b32 s39, -2
	s_add_u32 s14, s12, 0xfff80080
	s_addc_u32 s15, s13, -1
	s_add_i32 s40, 0, 0x10000
	v_add_u32_e32 v142, s40, v145
	ds_read_b128 v[148:151], v142
	ds_read_b128 v[152:155], v142 offset:1024
	ds_read_b128 v[156:159], v142 offset:2048
	ds_read_b128 v[160:163], v142 offset:3072
	s_cmp_eq_u32 s39, 28
	s_cselect_b32 s17, s1, s15
	s_cselect_b32 s16, s11, s14
	s_cselect_b32 s15, s3, s38
	s_cselect_b32 s14, s36, s37
	v_lshl_add_u64 v[142:143], s[12:13], 0, v[140:141]
	s_add_i32 m0, s24, 0xc000
	ds_read_b128 v[168:171], v146
	ds_read_b128 v[172:175], v146 offset:1024
	ds_read_b128 v[176:179], v146 offset:2048
	ds_read_b128 v[180:183], v146 offset:3072
	ds_read_b128 v[184:187], v146 offset:4096
	ds_read_b128 v[188:191], v146 offset:5120
	ds_read_b128 v[192:195], v146 offset:6144
	ds_read_b128 v[212:215], v146 offset:7168
	global_load_lds_dwordx4 v[142:143], off
	v_lshl_add_u64 v[142:143], s[12:13], 0, v[138:139]
	s_add_i32 m0, s24, 0xe000
	s_nop 0
	global_load_lds_dwordx4 v[142:143], off
	s_waitcnt lgkmcnt(8)
	s_barrier
	s_waitcnt lgkmcnt(0)
	s_setprio 1
	s_waitcnt lgkmcnt(0)
	v_mfma_f32_16x16x32_bf16 v[128:131], v[148:151], v[168:171], 0
	v_mfma_f32_16x16x32_bf16 v[128:131], v[152:155], v[172:175], v[128:131]
	v_mfma_f32_16x16x32_bf16 v[120:123], v[148:151], v[176:179], 0
	v_mfma_f32_16x16x32_bf16 v[120:123], v[152:155], v[180:183], v[120:123]
	v_mfma_f32_16x16x32_bf16 v[104:107], v[148:151], v[184:187], 0
	v_mfma_f32_16x16x32_bf16 v[104:107], v[152:155], v[188:191], v[104:107]
	v_mfma_f32_16x16x32_bf16 v[88:91], v[148:151], v[192:195], 0
	v_mfma_f32_16x16x32_bf16 v[88:91], v[152:155], v[212:215], v[88:91]
	v_mfma_f32_16x16x32_bf16 v[124:127], v[156:159], v[168:171], 0
	v_mfma_f32_16x16x32_bf16 v[124:127], v[160:163], v[172:175], v[124:127]
	v_mfma_f32_16x16x32_bf16 v[112:115], v[156:159], v[176:179], 0
	v_mfma_f32_16x16x32_bf16 v[112:115], v[160:163], v[180:183], v[112:115]
	v_mfma_f32_16x16x32_bf16 v[96:99], v[156:159], v[184:187], 0
	v_mfma_f32_16x16x32_bf16 v[96:99], v[160:163], v[188:191], v[96:99]
	v_mfma_f32_16x16x32_bf16 v[80:83], v[156:159], v[192:195], 0
	v_mfma_f32_16x16x32_bf16 v[80:83], v[160:163], v[212:215], v[80:83]
	s_setprio 0
	s_barrier
	s_add_i32 s42, 0, 0x14000
	v_add_u32_e32 v142, s42, v145
	s_add_i32 s40, s40, s19
	ds_read_b128 v[216:219], v142
	ds_read_b128 v[220:223], v142 offset:1024
	ds_read_b128 v[224:227], v142 offset:2048
	ds_read_b128 v[228:231], v142 offset:3072
	v_lshl_add_u64 v[142:143], s[14:15], 0, v[134:135]
	s_mov_b32 m0, s40
	v_lshl_add_u64 v[196:197], s[14:15], 0, v[0:1]
	global_load_lds_dwordx4 v[142:143], off
	s_add_i32 m0, s40, 0x2000
	s_nop 0
	global_load_lds_dwordx4 v[196:197], off
	s_barrier
	s_waitcnt lgkmcnt(0)
	s_setprio 1
	s_waitcnt lgkmcnt(0)
	v_mfma_f32_16x16x32_bf16 v[116:119], v[216:219], v[168:171], 0
	v_mfma_f32_16x16x32_bf16 v[116:119], v[220:223], v[172:175], v[116:119]
	v_mfma_f32_16x16x32_bf16 v[100:103], v[216:219], v[176:179], 0
	v_mfma_f32_16x16x32_bf16 v[100:103], v[220:223], v[180:183], v[100:103]
	v_mfma_f32_16x16x32_bf16 v[84:87], v[216:219], v[184:187], 0
	v_mfma_f32_16x16x32_bf16 v[84:87], v[220:223], v[188:191], v[84:87]
	v_mfma_f32_16x16x32_bf16 v[72:75], v[216:219], v[192:195], 0
	v_mfma_f32_16x16x32_bf16 v[72:75], v[220:223], v[212:215], v[72:75]
	v_mfma_f32_16x16x32_bf16 v[108:111], v[224:227], v[168:171], 0
	v_mfma_f32_16x16x32_bf16 v[108:111], v[228:231], v[172:175], v[108:111]
	v_mfma_f32_16x16x32_bf16 v[92:95], v[224:227], v[176:179], 0
	v_mfma_f32_16x16x32_bf16 v[92:95], v[228:231], v[180:183], v[92:95]
	v_mfma_f32_16x16x32_bf16 v[76:79], v[224:227], v[184:187], 0
	v_mfma_f32_16x16x32_bf16 v[76:79], v[228:231], v[188:191], v[76:79]
	v_mfma_f32_16x16x32_bf16 v[68:71], v[224:227], v[192:195], 0
	v_mfma_f32_16x16x32_bf16 v[68:71], v[228:231], v[212:215], v[68:71]
	s_setprio 0
	s_mov_b32 m0, s24
	v_lshl_add_u64 v[232:233], s[16:17], 0, v[136:137]
	s_barrier
	ds_read_b128 v[168:171], v146 offset:16384
	ds_read_b128 v[172:175], v146 offset:17408
	ds_read_b128 v[176:179], v146 offset:18432
	ds_read_b128 v[180:183], v146 offset:19456
	ds_read_b128 v[184:187], v146 offset:20480
	ds_read_b128 v[188:191], v146 offset:21504
	ds_read_b128 v[192:195], v146 offset:22528
	ds_read_b128 v[212:215], v146 offset:23552
	global_load_lds_dwordx4 v[232:233], off
	v_lshl_add_u64 v[234:235], s[16:17], 0, v[132:133]
	s_mov_b32 m0, s25
	s_nop 0
	global_load_lds_dwordx4 v[234:235], off
	s_barrier
	s_waitcnt lgkmcnt(0)
	s_setprio 1
	s_waitcnt lgkmcnt(0)
	v_mfma_f32_16x16x32_bf16 v[64:67], v[148:151], v[168:171], 0
	v_mfma_f32_16x16x32_bf16 v[64:67], v[152:155], v[172:175], v[64:67]
	v_mfma_f32_16x16x32_bf16 v[56:59], v[148:151], v[176:179], 0
	v_mfma_f32_16x16x32_bf16 v[56:59], v[152:155], v[180:183], v[56:59]
	v_mfma_f32_16x16x32_bf16 v[40:43], v[148:151], v[184:187], 0
	v_mfma_f32_16x16x32_bf16 v[40:43], v[152:155], v[188:191], v[40:43]
	v_mfma_f32_16x16x32_bf16 v[24:27], v[148:151], v[192:195], 0
	v_mfma_f32_16x16x32_bf16 v[24:27], v[152:155], v[212:215], v[24:27]
	v_mfma_f32_16x16x32_bf16 v[60:63], v[156:159], v[168:171], 0
	v_mfma_f32_16x16x32_bf16 v[60:63], v[160:163], v[172:175], v[60:63]
	v_mfma_f32_16x16x32_bf16 v[48:51], v[156:159], v[176:179], 0
	v_mfma_f32_16x16x32_bf16 v[48:51], v[160:163], v[180:183], v[48:51]
	v_mfma_f32_16x16x32_bf16 v[32:35], v[156:159], v[184:187], 0
	v_mfma_f32_16x16x32_bf16 v[32:35], v[160:163], v[188:191], v[32:35]
	v_mfma_f32_16x16x32_bf16 v[16:19], v[156:159], v[192:195], 0
	v_mfma_f32_16x16x32_bf16 v[16:19], v[160:163], v[212:215], v[16:19]
	s_setprio 0
	s_barrier
; #define PG8_WAIT_V(n) asm volatile("s_waitcnt vmcnt(" #n ")" ::: "memory")
; #define PG8_WAIT_L(n) asm volatile("s_waitcnt lgkmcnt(" #n ")" ::: "memory")
; #define PG8_BAR __builtin_amdgcn_s_barrier()
; #define PG8_SCHED __builtin_amdgcn_sched_barrier(0)
; template <class Epi, class AddrA, class AddrB>
; __device__ __forceinline__ void gemm_phase(const Sched S, const int lda, const int ldb, const int K, const AddrA addrA,
;                                            const AddrB addrB, const Epi E) {
;     ...
;       PG8_STAGE(PG8_SB(0, 1), b2 + hstepB, voffB);
;       PG8_WAIT_V(6); PG8_BAR; PG8_MMA(1, 1, At, B1); PG8_BAR;
;       PG8_LDB(B0, 1, 0); PG8_SCHED; PG8_LDA(At, 1, 0); PG8_STAGE(PG8_SA(0, 1), a2 + hstepA, voffA);
;       PG8_WAIT_L(8); PG8_BAR; PG8_WAIT_L(0); PG8_MMA(0, 0, At, B0); PG8_BAR; PG8_SCHED;
;       PG8_LDB(B1, 1, 1); PG8_STAGE(PG8_SB(1, 0), b3, voffB);
;       PG8_BAR; PG8_WAIT_L(0); PG8_MMA(0, 1, At, B1); PG8_BAR;
;       PG8_LDA(At, 1, 1); PG8_STAGE(PG8_SA(1, 0), a3, voffA);
	s_add_u32 s40, s14, 0x80000
	s_addc_u32 s41, s15, 0
	s_add_i32 s42, s42, s19
	v_lshl_add_u64 v[148:149], s[40:41], 0, v[134:135]
	s_mov_b32 m0, s42
	s_nop 0
	global_load_lds_dwordx4 v[148:149], off
	v_lshl_add_u64 v[148:149], s[40:41], 0, v[0:1]
	s_add_i32 m0, s42, 0x2000
	s_nop 0
	global_load_lds_dwordx4 v[148:149], off
	s_waitcnt vmcnt(6)
	s_barrier
	s_setprio 1
	v_mfma_f32_16x16x32_bf16 v[52:55], v[216:219], v[168:171], 0
	v_mfma_f32_16x16x32_bf16 v[52:55], v[220:223], v[172:175], v[52:55]
	v_mfma_f32_16x16x32_bf16 v[36:39], v[216:219], v[176:179], 0
	v_mfma_f32_16x16x32_bf16 v[36:39], v[220:223], v[180:183], v[36:39]
	v_mfma_f32_16x16x32_bf16 v[20:23], v[216:219], v[184:187], 0
	v_mfma_f32_16x16x32_bf16 v[20:23], v[220:223], v[188:191], v[20:23]
	v_mfma_f32_16x16x32_bf16 v[8:11], v[216:219], v[192:195], 0
	v_mfma_f32_16x16x32_bf16 v[8:11], v[220:223], v[212:215], v[8:11]
	v_mfma_f32_16x16x32_bf16 v[44:47], v[224:227], v[168:171], 0
	v_mfma_f32_16x16x32_bf16 v[44:47], v[228:231], v[172:175], v[44:47]
	v_mfma_f32_16x16x32_bf16 v[28:31], v[224:227], v[176:179], 0
	v_mfma_f32_16x16x32_bf16 v[28:31], v[228:231], v[180:183], v[28:31]
	v_mfma_f32_16x16x32_bf16 v[12:15], v[224:227], v[184:187], 0
	v_mfma_f32_16x16x32_bf16 v[12:15], v[228:231], v[188:191], v[12:15]
	v_mfma_f32_16x16x32_bf16 v[4:7], v[224:227], v[192:195], 0
	v_mfma_f32_16x16x32_bf16 v[4:7], v[228:231], v[212:215], v[4:7]
	s_setprio 0
	s_add_i32 s40, 0, 0x18000
	v_add_u32_e32 v147, s40, v145
	s_barrier
	ds_read_b128 v[148:151], v147
	ds_read_b128 v[152:155], v147 offset:1024
	ds_read_b128 v[156:159], v147 offset:2048
	ds_read_b128 v[160:163], v147 offset:3072
	s_add_u32 s16, s16, 0x80000
	s_addc_u32 s17, s17, 0
	s_mov_b32 m0, s26
	v_lshl_add_u64 v[216:217], s[16:17], 0, v[136:137]
	ds_read_b128 v[168:171], v146 offset:32768
	ds_read_b128 v[172:175], v146 offset:33792
	ds_read_b128 v[176:179], v146 offset:34816
	ds_read_b128 v[180:183], v146 offset:35840
	ds_read_b128 v[184:187], v146 offset:36864
	ds_read_b128 v[188:191], v146 offset:37888
	ds_read_b128 v[192:195], v146 offset:38912
	ds_read_b128 v[212:215], v146 offset:39936
	global_load_lds_dwordx4 v[216:217], off
	v_lshl_add_u64 v[216:217], s[16:17], 0, v[132:133]
	s_mov_b32 m0, s27
	s_nop 0
	global_load_lds_dwordx4 v[216:217], off
	s_waitcnt lgkmcnt(8)
	s_barrier
	s_waitcnt lgkmcnt(0)
	s_setprio 1
	s_waitcnt lgkmcnt(0)
	v_mfma_f32_16x16x32_bf16 v[128:131], v[148:151], v[168:171], v[128:131]
	v_mfma_f32_16x16x32_bf16 v[128:131], v[152:155], v[172:175], v[128:131]
	v_mfma_f32_16x16x32_bf16 v[120:123], v[148:151], v[176:179], v[120:123]
	v_mfma_f32_16x16x32_bf16 v[120:123], v[152:155], v[180:183], v[120:123]
	v_mfma_f32_16x16x32_bf16 v[104:107], v[148:151], v[184:187], v[104:107]
	v_mfma_f32_16x16x32_bf16 v[104:107], v[152:155], v[188:191], v[104:107]
	v_mfma_f32_16x16x32_bf16 v[88:91], v[148:151], v[192:195], v[88:91]
	v_mfma_f32_16x16x32_bf16 v[88:91], v[152:155], v[212:215], v[88:91]
	v_mfma_f32_16x16x32_bf16 v[124:127], v[156:159], v[168:171], v[124:127]
	v_mfma_f32_16x16x32_bf16 v[124:127], v[160:163], v[172:175], v[124:127]
	v_mfma_f32_16x16x32_bf16 v[112:115], v[156:159], v[176:179], v[112:115]
	v_mfma_f32_16x16x32_bf16 v[112:115], v[160:163], v[180:183], v[112:115]
	v_mfma_f32_16x16x32_bf16 v[96:99], v[156:159], v[184:187], v[96:99]
	v_mfma_f32_16x16x32_bf16 v[96:99], v[160:163], v[188:191], v[96:99]
	v_mfma_f32_16x16x32_bf16 v[80:83], v[156:159], v[192:195], v[80:83]
	v_mfma_f32_16x16x32_bf16 v[80:83], v[160:163], v[212:215], v[80:83]
	s_setprio 0
	s_barrier
	s_add_i32 s16, 0, 0x1c000
	s_add_i32 s17, s40, s19
	v_add_u32_e32 v147, s16, v145
	v_lshl_add_u64 v[142:143], v[142:143], 0, s[52:53]
	s_mov_b32 m0, s17
	ds_read_b128 v[216:219], v147
	ds_read_b128 v[220:223], v147 offset:1024
	ds_read_b128 v[224:227], v147 offset:2048
	ds_read_b128 v[228:231], v147 offset:3072
	global_load_lds_dwordx4 v[142:143], off
	v_lshl_add_u64 v[142:143], v[196:197], 0, s[52:53]
	s_add_i32 m0, s17, 0x2000
	s_nop 0
	global_load_lds_dwordx4 v[142:143], off
	s_barrier
; #define PG8_WAIT_V(n) asm volatile("s_waitcnt vmcnt(" #n ")" ::: "memory")
; #define PG8_WAIT_L(n) asm volatile("s_waitcnt lgkmcnt(" #n ")" ::: "memory")
; #define PG8_BAR __builtin_amdgcn_s_barrier()
; #define PG8_SCHED __builtin_amdgcn_sched_barrier(0)
; template <class Epi, class AddrA, class AddrB>
; __device__ __forceinline__ void gemm_phase(const Sched S, const int lda, const int ldb, const int K, const AddrA addrA,
;                                            const AddrB addrB, const Epi E) {
;     ...
;       PG8_BAR; PG8_WAIT_L(0); PG8_MMA(1, 0, At, B0); PG8_BAR; PG8_SCHED;
;       PG8_STAGE(PG8_SB(1, 1), b3 + hstepB, voffB);
;       PG8_WAIT_V(6); PG8_BAR; PG8_MMA(1, 1, At, B1); PG8_BAR;
	s_waitcnt lgkmcnt(0)
	s_setprio 1
	s_waitcnt lgkmcnt(0)
	v_mfma_f32_16x16x32_bf16 v[116:119], v[216:219], v[168:171], v[116:119]
	v_mfma_f32_16x16x32_bf16 v[116:119], v[220:223], v[172:175], v[116:119]
	v_mfma_f32_16x16x32_bf16 v[100:103], v[216:219], v[176:179], v[100:103]
	v_mfma_f32_16x16x32_bf16 v[100:103], v[220:223], v[180:183], v[100:103]
	v_mfma_f32_16x16x32_bf16 v[84:87], v[216:219], v[184:187], v[84:87]
	v_mfma_f32_16x16x32_bf16 v[84:87], v[220:223], v[188:191], v[84:87]
	v_mfma_f32_16x16x32_bf16 v[72:75], v[216:219], v[192:195], v[72:75]
	v_mfma_f32_16x16x32_bf16 v[72:75], v[220:223], v[212:215], v[72:75]
	v_mfma_f32_16x16x32_bf16 v[108:111], v[224:227], v[168:171], v[108:111]
	v_mfma_f32_16x16x32_bf16 v[108:111], v[228:231], v[172:175], v[108:111]
	v_mfma_f32_16x16x32_bf16 v[92:95], v[224:227], v[176:179], v[92:95]
	v_mfma_f32_16x16x32_bf16 v[92:95], v[228:231], v[180:183], v[92:95]
	v_mfma_f32_16x16x32_bf16 v[76:79], v[224:227], v[184:187], v[76:79]
	v_mfma_f32_16x16x32_bf16 v[76:79], v[228:231], v[188:191], v[76:79]
	v_mfma_f32_16x16x32_bf16 v[68:71], v[224:227], v[192:195], v[68:71]
	v_mfma_f32_16x16x32_bf16 v[68:71], v[228:231], v[212:215], v[68:71]
	s_setprio 0
	s_mov_b32 m0, s30
	v_lshl_add_u64 v[142:143], v[232:233], 0, s[52:53]
	s_barrier
	ds_read_b128 v[168:171], v146 offset:49152
	ds_read_b128 v[172:175], v146 offset:50176
	ds_read_b128 v[176:179], v146 offset:51200
	ds_read_b128 v[180:183], v146 offset:52224
	ds_read_b128 v[184:187], v146 offset:53248
	ds_read_b128 v[188:191], v146 offset:54272
	ds_read_b128 v[192:195], v146 offset:55296
	ds_read_b128 v[212:215], v146 offset:56320
	global_load_lds_dwordx4 v[142:143], off
	v_lshl_add_u64 v[142:143], v[234:235], 0, s[52:53]
	s_mov_b32 m0, s31
	s_nop 0
	global_load_lds_dwordx4 v[142:143], off
	s_barrier
	s_waitcnt lgkmcnt(0)
	s_setprio 1
	s_waitcnt lgkmcnt(0)
	v_mfma_f32_16x16x32_bf16 v[64:67], v[148:151], v[168:171], v[64:67]
	v_mfma_f32_16x16x32_bf16 v[64:67], v[152:155], v[172:175], v[64:67]
	v_mfma_f32_16x16x32_bf16 v[56:59], v[148:151], v[176:179], v[56:59]
	v_mfma_f32_16x16x32_bf16 v[56:59], v[152:155], v[180:183], v[56:59]
	v_mfma_f32_16x16x32_bf16 v[40:43], v[148:151], v[184:187], v[40:43]
	v_mfma_f32_16x16x32_bf16 v[40:43], v[152:155], v[188:191], v[40:43]
	v_mfma_f32_16x16x32_bf16 v[24:27], v[148:151], v[192:195], v[24:27]
	v_mfma_f32_16x16x32_bf16 v[24:27], v[152:155], v[212:215], v[24:27]
	v_mfma_f32_16x16x32_bf16 v[60:63], v[156:159], v[168:171], v[60:63]
	v_mfma_f32_16x16x32_bf16 v[60:63], v[160:163], v[172:175], v[60:63]
	v_mfma_f32_16x16x32_bf16 v[48:51], v[156:159], v[176:179], v[48:51]
	v_mfma_f32_16x16x32_bf16 v[48:51], v[160:163], v[180:183], v[48:51]
	v_mfma_f32_16x16x32_bf16 v[32:35], v[156:159], v[184:187], v[32:35]
	v_mfma_f32_16x16x32_bf16 v[32:35], v[160:163], v[188:191], v[32:35]
	v_mfma_f32_16x16x32_bf16 v[16:19], v[156:159], v[192:195], v[16:19]
	v_mfma_f32_16x16x32_bf16 v[16:19], v[160:163], v[212:215], v[16:19]
	s_setprio 0
	s_barrier
	s_add_u32 s14, s14, 0x80080
	s_addc_u32 s15, s15, 0
	s_add_i32 s16, s16, s19
	v_lshl_add_u64 v[142:143], s[14:15], 0, v[134:135]
	s_mov_b32 m0, s16
	s_nop 0
	global_load_lds_dwordx4 v[142:143], off
	v_lshl_add_u64 v[142:143], s[14:15], 0, v[0:1]
	s_add_i32 m0, s16, 0x2000
	s_nop 0
	global_load_lds_dwordx4 v[142:143], off
	s_waitcnt vmcnt(6)
	s_barrier
	s_setprio 1
	v_mfma_f32_16x16x32_bf16 v[52:55], v[216:219], v[168:171], v[52:55]
	v_mfma_f32_16x16x32_bf16 v[52:55], v[220:223], v[172:175], v[52:55]
	v_mfma_f32_16x16x32_bf16 v[36:39], v[216:219], v[176:179], v[36:39]
	v_mfma_f32_16x16x32_bf16 v[36:39], v[220:223], v[180:183], v[36:39]
	v_mfma_f32_16x16x32_bf16 v[20:23], v[216:219], v[184:187], v[20:23]
	v_mfma_f32_16x16x32_bf16 v[20:23], v[220:223], v[188:191], v[20:23]
	v_mfma_f32_16x16x32_bf16 v[8:11], v[216:219], v[192:195], v[8:11]
	v_mfma_f32_16x16x32_bf16 v[8:11], v[220:223], v[212:215], v[8:11]
	v_mfma_f32_16x16x32_bf16 v[44:47], v[224:227], v[168:171], v[44:47]
	v_mfma_f32_16x16x32_bf16 v[44:47], v[228:231], v[172:175], v[44:47]
	v_mfma_f32_16x16x32_bf16 v[28:31], v[224:227], v[176:179], v[28:31]
	v_mfma_f32_16x16x32_bf16 v[28:31], v[228:231], v[180:183], v[28:31]
	v_mfma_f32_16x16x32_bf16 v[12:15], v[224:227], v[184:187], v[12:15]
	v_mfma_f32_16x16x32_bf16 v[12:15], v[228:231], v[188:191], v[12:15]
	v_mfma_f32_16x16x32_bf16 v[4:7], v[224:227], v[192:195], v[4:7]
	v_mfma_f32_16x16x32_bf16 v[4:7], v[228:231], v[212:215], v[4:7]
	s_setprio 0
	s_add_i32 s39, s39, 2
	s_add_u32 s37, s37, 0x100
	s_addc_u32 s38, s38, 0
	s_add_u32 s12, s12, 0x100
	s_addc_u32 s13, s13, 0
	s_cmp_gt_u32 s39, 29
	s_barrier

; #define PG8_WAIT_L(n) asm volatile("s_waitcnt lgkmcnt(" #n ")" ::: "memory")
; #define PG8_BAR __builtin_amdgcn_s_barrier()
; #define PG8_SCHED __builtin_amdgcn_sched_barrier(0)
; template <class Epi, class AddrA, class AddrB>
; __device__ __forceinline__ void gemm_phase(const Sched S, const int lda, const int ldb, const int K, const AddrA addrA,
;                                            const AddrB addrB, const Epi E) {
;     ...
;     const bool has_next = S.next(ui + 1, nxt);
;     const char* nA = has_next ? addrA(nxt) : cA;
;     const char* nB = has_next ? addrB(nxt) : cB;
;     for (int t = 0; t < nt; t += 2) {
;       const bool last = (t == nt - 2);
;       const char* a1 = cA + (size_t)(t + 1) * kstep;
;       const char* a2 = last ? nA : cA + (size_t)(t + 2) * kstep;
;       const char* b2 = last ? nB : cB + (size_t)(t + 2) * kstep;
;       const char* a3 = a2 + kstep;
;       const char* b3 = b2 + kstep;
;       PG8_LDB(B0, 0, 0); PG8_SCHED; PG8_LDA(At, 0, 0); PG8_STAGE(PG8_SA(1, 1), a1 + hstepA, voffA);
;       PG8_WAIT_L(8); PG8_BAR; PG8_WAIT_L(0); PG8_MMA(0, 0, At, B0); PG8_BAR; PG8_SCHED;
;       PG8_LDB(B1, 0, 1); PG8_STAGE(PG8_SB(0, 0), b2, voffB);
;       PG8_BAR; PG8_WAIT_L(0); PG8_MMA(0, 1, At, B1); PG8_BAR;
;       PG8_LDA(At, 0, 1); PG8_STAGE(PG8_SA(0, 0), a2, voffA);
;       PG8_BAR; PG8_WAIT_L(0); PG8_MMA(1, 0, At, B0); PG8_BAR; PG8_SCHED;
.LBB0_484:
	s_ashr_i32 s15, s14, 31
	s_lshl_b64 s[20:21], s[14:15], 20
	s_add_u32 s3, s25, s20
	s_addc_u32 s15, s26, s21
	s_lshl_b32 s17, s16, 8
	s_and_b32 s20, s17, 0xfffffe00
	s_ashr_i32 s21, s20, 31
	s_lshl_b64 s[20:21], s[20:21], 1
	s_add_u32 s20, s3, s20
	s_addc_u32 s21, s15, s21
	s_and_b64 s[22:23], s[10:11], exec
	s_cselect_b32 s3, s21, s7
	s_cselect_b32 s15, s20, s6
	s_ashr_i32 s17, s16, 31
	s_lshl_b64 s[22:23], s[16:17], 18
	s_add_u32 s22, s27, s22
	s_addc_u32 s23, s28, s23
	s_and_b64 s[10:11], s[10:11], exec
	s_cselect_b32 s17, s23, s5
	s_cselect_b32 s40, s22, s4
	s_add_u32 s41, s4, 0x100
	s_addc_u32 s42, s5, 0
	s_add_u32 s4, s6, 0x80080
	s_addc_u32 s5, s7, 0
	s_mov_b32 s43, -2
	s_add_u32 s6, s4, 0xfff80080
	s_addc_u32 s7, s5, -1
	s_add_i32 s44, 0, 0x10000
	v_add_u32_e32 v2, s44, v167
	ds_read_b128 v[92:95], v2
	ds_read_b128 v[100:103], v2 offset:1024
	ds_read_b128 v[132:135], v2 offset:2048
	ds_read_b128 v[144:147], v2 offset:3072
	s_cmp_eq_u32 s43, 4
	s_cselect_b32 s11, s3, s7
	s_cselect_b32 s10, s15, s6
	s_cselect_b32 s7, s17, s42
	s_cselect_b32 s6, s40, s41
	v_lshl_add_u64 v[196:197], s[4:5], 0, v[172:173]
	s_add_i32 m0, s30, 0xc000
	ds_read_b128 v[148:151], v169
	ds_read_b128 v[152:155], v169 offset:1024
	ds_read_b128 v[176:179], v169 offset:2048
	ds_read_b128 v[180:183], v169 offset:3072
	ds_read_b128 v[184:187], v169 offset:4096
	ds_read_b128 v[188:191], v169 offset:5120
	ds_read_b128 v[192:195], v169 offset:6144
	ds_read_b128 v[212:215], v169 offset:7168
	global_load_lds_dwordx4 v[196:197], off
	v_lshl_add_u64 v[196:197], s[4:5], 0, v[170:171]
	s_add_i32 m0, s30, 0xe000
	s_nop 0
	global_load_lds_dwordx4 v[196:197], off
	s_waitcnt lgkmcnt(8)
	s_barrier
	s_waitcnt lgkmcnt(0)
	s_setprio 1
	s_waitcnt lgkmcnt(0)
	v_mfma_f32_16x16x32_bf16 v[140:143], v[92:95], v[148:151], 0
	v_mfma_f32_16x16x32_bf16 v[140:143], v[100:103], v[152:155], v[140:143]
	v_mfma_f32_16x16x32_bf16 v[128:131], v[92:95], v[176:179], 0
	v_mfma_f32_16x16x32_bf16 v[128:131], v[100:103], v[180:183], v[128:131]
	v_mfma_f32_16x16x32_bf16 v[120:123], v[92:95], v[184:187], 0
	v_mfma_f32_16x16x32_bf16 v[120:123], v[100:103], v[188:191], v[120:123]
	v_mfma_f32_16x16x32_bf16 v[112:115], v[92:95], v[192:195], 0
	v_mfma_f32_16x16x32_bf16 v[112:115], v[100:103], v[212:215], v[112:115]
	v_mfma_f32_16x16x32_bf16 v[136:139], v[132:135], v[148:151], 0
	v_mfma_f32_16x16x32_bf16 v[136:139], v[144:147], v[152:155], v[136:139]
	v_mfma_f32_16x16x32_bf16 v[124:127], v[132:135], v[176:179], 0
	v_mfma_f32_16x16x32_bf16 v[124:127], v[144:147], v[180:183], v[124:127]
	v_mfma_f32_16x16x32_bf16 v[116:119], v[132:135], v[184:187], 0
	v_mfma_f32_16x16x32_bf16 v[116:119], v[144:147], v[188:191], v[116:119]
	v_mfma_f32_16x16x32_bf16 v[108:111], v[132:135], v[192:195], 0
	v_mfma_f32_16x16x32_bf16 v[108:111], v[144:147], v[212:215], v[108:111]
	s_setprio 0
	s_barrier
	s_add_i32 s46, 0, 0x14000
	s_add_i32 s44, s44, s29
	v_add_u32_e32 v2, s46, v167
	v_lshl_add_u64 v[196:197], s[6:7], 0, v[158:159]
	s_mov_b32 m0, s44
	ds_read_b128 v[216:219], v2
	ds_read_b128 v[220:223], v2 offset:1024
	ds_read_b128 v[224:227], v2 offset:2048
	ds_read_b128 v[228:231], v2 offset:3072
	global_load_lds_dwordx4 v[196:197], off
	v_lshl_add_u64 v[232:233], s[6:7], 0, v[0:1]
	s_add_i32 m0, s44, 0x2000
	s_nop 0
	global_load_lds_dwordx4 v[232:233], off
	s_barrier
	s_waitcnt lgkmcnt(0)
	s_setprio 1
	s_waitcnt lgkmcnt(0)
	v_mfma_f32_16x16x32_bf16 v[64:67], v[216:219], v[148:151], 0
	v_mfma_f32_16x16x32_bf16 v[64:67], v[220:223], v[152:155], v[64:67]
	v_mfma_f32_16x16x32_bf16 v[56:59], v[216:219], v[176:179], 0
	v_mfma_f32_16x16x32_bf16 v[56:59], v[220:223], v[180:183], v[56:59]
	v_mfma_f32_16x16x32_bf16 v[48:51], v[216:219], v[184:187], 0
	v_mfma_f32_16x16x32_bf16 v[48:51], v[220:223], v[188:191], v[48:51]
	v_mfma_f32_16x16x32_bf16 v[40:43], v[216:219], v[192:195], 0
	v_mfma_f32_16x16x32_bf16 v[40:43], v[220:223], v[212:215], v[40:43]
	v_mfma_f32_16x16x32_bf16 v[60:63], v[224:227], v[148:151], 0
	v_mfma_f32_16x16x32_bf16 v[60:63], v[228:231], v[152:155], v[60:63]
	v_mfma_f32_16x16x32_bf16 v[52:55], v[224:227], v[176:179], 0
	v_mfma_f32_16x16x32_bf16 v[52:55], v[228:231], v[180:183], v[52:55]
	v_mfma_f32_16x16x32_bf16 v[44:47], v[224:227], v[184:187], 0
	v_mfma_f32_16x16x32_bf16 v[44:47], v[228:231], v[188:191], v[44:47]
	v_mfma_f32_16x16x32_bf16 v[36:39], v[224:227], v[192:195], 0
	v_mfma_f32_16x16x32_bf16 v[36:39], v[228:231], v[212:215], v[36:39]
	s_setprio 0
	s_mov_b32 m0, s30
	v_lshl_add_u64 v[234:235], s[10:11], 0, v[160:161]
	s_barrier
	ds_read_b128 v[148:151], v169 offset:16384
	ds_read_b128 v[152:155], v169 offset:17408
	ds_read_b128 v[176:179], v169 offset:18432
	ds_read_b128 v[180:183], v169 offset:19456
	ds_read_b128 v[184:187], v169 offset:20480
	ds_read_b128 v[188:191], v169 offset:21504
	ds_read_b128 v[192:195], v169 offset:22528
	ds_read_b128 v[212:215], v169 offset:23552
	global_load_lds_dwordx4 v[234:235], off
	v_lshl_add_u64 v[236:237], s[10:11], 0, v[156:157]
	s_mov_b32 m0, s31
	s_nop 0
	global_load_lds_dwordx4 v[236:237], off
	s_barrier
	s_waitcnt lgkmcnt(0)
	s_setprio 1
	s_waitcnt lgkmcnt(0)
	v_mfma_f32_16x16x32_bf16 v[104:107], v[92:95], v[148:151], 0
	v_mfma_f32_16x16x32_bf16 v[104:107], v[100:103], v[152:155], v[104:107]
	v_mfma_f32_16x16x32_bf16 v[88:91], v[92:95], v[176:179], 0
	v_mfma_f32_16x16x32_bf16 v[88:91], v[100:103], v[180:183], v[88:91]
	v_mfma_f32_16x16x32_bf16 v[80:83], v[92:95], v[184:187], 0
	v_mfma_f32_16x16x32_bf16 v[80:83], v[100:103], v[188:191], v[80:83]
	v_mfma_f32_16x16x32_bf16 v[72:75], v[92:95], v[192:195], 0
	v_mfma_f32_16x16x32_bf16 v[72:75], v[100:103], v[212:215], v[72:75]
	v_mfma_f32_16x16x32_bf16 v[96:99], v[132:135], v[148:151], 0
	v_mfma_f32_16x16x32_bf16 v[96:99], v[144:147], v[152:155], v[96:99]
	v_mfma_f32_16x16x32_bf16 v[84:87], v[132:135], v[176:179], 0
	v_mfma_f32_16x16x32_bf16 v[84:87], v[144:147], v[180:183], v[84:87]
	v_mfma_f32_16x16x32_bf16 v[76:79], v[132:135], v[184:187], 0
	v_mfma_f32_16x16x32_bf16 v[76:79], v[144:147], v[188:191], v[76:79]
	v_mfma_f32_16x16x32_bf16 v[68:71], v[132:135], v[192:195], 0
	v_mfma_f32_16x16x32_bf16 v[68:71], v[144:147], v[212:215], v[68:71]
	s_setprio 0
	s_barrier
; #define PG8_WAIT_V(n) asm volatile("s_waitcnt vmcnt(" #n ")" ::: "memory")
; #define PG8_WAIT_L(n) asm volatile("s_waitcnt lgkmcnt(" #n ")" ::: "memory")
; #define PG8_BAR __builtin_amdgcn_s_barrier()
; #define PG8_SCHED __builtin_amdgcn_sched_barrier(0)
; template <class Epi, class AddrA, class AddrB>
; __device__ __forceinline__ void gemm_phase(const Sched S, const int lda, const int ldb, const int K, const AddrA addrA,
;                                            const AddrB addrB, const Epi E) {
;     ...
;       PG8_STAGE(PG8_SB(0, 1), b2 + hstepB, voffB);
;       PG8_WAIT_V(6); PG8_BAR; PG8_MMA(1, 1, At, B1); PG8_BAR;
;       PG8_LDB(B0, 1, 0); PG8_SCHED; PG8_LDA(At, 1, 0); PG8_STAGE(PG8_SA(0, 1), a2 + hstepA, voffA);
;       PG8_WAIT_L(8); PG8_BAR; PG8_WAIT_L(0); PG8_MMA(0, 0, At, B0); PG8_BAR; PG8_SCHED;
;       PG8_LDB(B1, 1, 1); PG8_STAGE(PG8_SB(1, 0), b3, voffB);
;       PG8_BAR; PG8_WAIT_L(0); PG8_MMA(0, 1, At, B1); PG8_BAR;
;       PG8_LDA(At, 1, 1); PG8_STAGE(PG8_SA(1, 0), a3, voffA);
	s_add_u32 s44, s6, 0x20000
	s_addc_u32 s45, s7, 0
	s_add_i32 s46, s46, s29
	v_lshl_add_u64 v[92:93], s[44:45], 0, v[158:159]
	s_mov_b32 m0, s46
	s_nop 0
	global_load_lds_dwordx4 v[92:93], off
	v_lshl_add_u64 v[92:93], s[44:45], 0, v[0:1]
	s_add_i32 m0, s46, 0x2000
	s_nop 0
	global_load_lds_dwordx4 v[92:93], off
	s_waitcnt vmcnt(6)
	s_barrier
	s_setprio 1
	v_mfma_f32_16x16x32_bf16 v[32:35], v[216:219], v[148:151], 0
	v_mfma_f32_16x16x32_bf16 v[32:35], v[220:223], v[152:155], v[32:35]
	v_mfma_f32_16x16x32_bf16 v[24:27], v[216:219], v[176:179], 0
	v_mfma_f32_16x16x32_bf16 v[24:27], v[220:223], v[180:183], v[24:27]
	v_mfma_f32_16x16x32_bf16 v[16:19], v[216:219], v[184:187], 0
	v_mfma_f32_16x16x32_bf16 v[16:19], v[220:223], v[188:191], v[16:19]
	v_mfma_f32_16x16x32_bf16 v[8:11], v[216:219], v[192:195], 0
	v_mfma_f32_16x16x32_bf16 v[8:11], v[220:223], v[212:215], v[8:11]
	v_mfma_f32_16x16x32_bf16 v[28:31], v[224:227], v[148:151], 0
	v_mfma_f32_16x16x32_bf16 v[28:31], v[228:231], v[152:155], v[28:31]
	v_mfma_f32_16x16x32_bf16 v[20:23], v[224:227], v[176:179], 0
	v_mfma_f32_16x16x32_bf16 v[20:23], v[228:231], v[180:183], v[20:23]
	v_mfma_f32_16x16x32_bf16 v[12:15], v[224:227], v[184:187], 0
	v_mfma_f32_16x16x32_bf16 v[12:15], v[228:231], v[188:191], v[12:15]
	v_mfma_f32_16x16x32_bf16 v[4:7], v[224:227], v[192:195], 0
	v_mfma_f32_16x16x32_bf16 v[4:7], v[228:231], v[212:215], v[4:7]
	s_setprio 0
	s_add_i32 s44, 0, 0x18000
	v_add_u32_e32 v2, s44, v167
	s_barrier
	ds_read_b128 v[92:95], v2
	ds_read_b128 v[100:103], v2 offset:1024
	ds_read_b128 v[132:135], v2 offset:2048
	ds_read_b128 v[144:147], v2 offset:3072
	s_add_u32 s10, s10, 0x80000
	s_addc_u32 s11, s11, 0
	s_mov_b32 m0, s34
	v_lshl_add_u64 v[216:217], s[10:11], 0, v[160:161]
	ds_read_b128 v[148:151], v169 offset:32768
	ds_read_b128 v[152:155], v169 offset:33792
	ds_read_b128 v[176:179], v169 offset:34816
	ds_read_b128 v[180:183], v169 offset:35840
	ds_read_b128 v[184:187], v169 offset:36864
	ds_read_b128 v[188:191], v169 offset:37888
	ds_read_b128 v[192:195], v169 offset:38912
	ds_read_b128 v[212:215], v169 offset:39936
	global_load_lds_dwordx4 v[216:217], off
	v_lshl_add_u64 v[216:217], s[10:11], 0, v[156:157]
	s_mov_b32 m0, s35
	s_nop 0
	global_load_lds_dwordx4 v[216:217], off
	s_waitcnt lgkmcnt(8)
	s_barrier
	s_waitcnt lgkmcnt(0)
	s_setprio 1
	s_waitcnt lgkmcnt(0)
	v_mfma_f32_16x16x32_bf16 v[140:143], v[92:95], v[148:151], v[140:143]
	v_mfma_f32_16x16x32_bf16 v[140:143], v[100:103], v[152:155], v[140:143]
	v_mfma_f32_16x16x32_bf16 v[128:131], v[92:95], v[176:179], v[128:131]
	v_mfma_f32_16x16x32_bf16 v[128:131], v[100:103], v[180:183], v[128:131]
	v_mfma_f32_16x16x32_bf16 v[120:123], v[92:95], v[184:187], v[120:123]
	v_mfma_f32_16x16x32_bf16 v[120:123], v[100:103], v[188:191], v[120:123]
	v_mfma_f32_16x16x32_bf16 v[112:115], v[92:95], v[192:195], v[112:115]
	v_mfma_f32_16x16x32_bf16 v[112:115], v[100:103], v[212:215], v[112:115]
	v_mfma_f32_16x16x32_bf16 v[136:139], v[132:135], v[148:151], v[136:139]
	v_mfma_f32_16x16x32_bf16 v[136:139], v[144:147], v[152:155], v[136:139]
	v_mfma_f32_16x16x32_bf16 v[124:127], v[132:135], v[176:179], v[124:127]
	v_mfma_f32_16x16x32_bf16 v[124:127], v[144:147], v[180:183], v[124:127]
	v_mfma_f32_16x16x32_bf16 v[116:119], v[132:135], v[184:187], v[116:119]
	v_mfma_f32_16x16x32_bf16 v[116:119], v[144:147], v[188:191], v[116:119]
	v_mfma_f32_16x16x32_bf16 v[108:111], v[132:135], v[192:195], v[108:111]
	v_mfma_f32_16x16x32_bf16 v[108:111], v[144:147], v[212:215], v[108:111]
	s_setprio 0
	s_barrier
	s_add_i32 s10, 0, 0x1c000
	s_add_i32 s11, s44, s29
	v_add_u32_e32 v2, s10, v167
	v_lshl_add_u64 v[196:197], v[196:197], 0, s[52:53]
	s_mov_b32 m0, s11
	ds_read_b128 v[216:219], v2
	ds_read_b128 v[220:223], v2 offset:1024
	ds_read_b128 v[224:227], v2 offset:2048
	ds_read_b128 v[228:231], v2 offset:3072
	global_load_lds_dwordx4 v[196:197], off
	v_lshl_add_u64 v[196:197], v[232:233], 0, s[52:53]
	s_add_i32 m0, s11, 0x2000
	s_nop 0
	global_load_lds_dwordx4 v[196:197], off
	s_barrier
; #define PG8_WAIT_V(n) asm volatile("s_waitcnt vmcnt(" #n ")" ::: "memory")
; #define PG8_WAIT_L(n) asm volatile("s_waitcnt lgkmcnt(" #n ")" ::: "memory")
; #define PG8_BAR __builtin_amdgcn_s_barrier()
; #define PG8_SCHED __builtin_amdgcn_sched_barrier(0)
; template <class Epi, class AddrA, class AddrB>
; __device__ __forceinline__ void gemm_phase(const Sched S, const int lda, const int ldb, const int K, const AddrA addrA,
;                                            const AddrB addrB, const Epi E) {
;     ...
;       PG8_BAR; PG8_WAIT_L(0); PG8_MMA(1, 0, At, B0); PG8_BAR; PG8_SCHED;
;       PG8_STAGE(PG8_SB(1, 1), b3 + hstepB, voffB);
;       PG8_WAIT_V(6); PG8_BAR; PG8_MMA(1, 1, At, B1); PG8_BAR;
	s_waitcnt lgkmcnt(0)
	s_setprio 1
	s_waitcnt lgkmcnt(0)
	v_mfma_f32_16x16x32_bf16 v[64:67], v[216:219], v[148:151], v[64:67]
	v_mfma_f32_16x16x32_bf16 v[64:67], v[220:223], v[152:155], v[64:67]
	v_mfma_f32_16x16x32_bf16 v[56:59], v[216:219], v[176:179], v[56:59]
	v_mfma_f32_16x16x32_bf16 v[56:59], v[220:223], v[180:183], v[56:59]
	v_mfma_f32_16x16x32_bf16 v[48:51], v[216:219], v[184:187], v[48:51]
	v_mfma_f32_16x16x32_bf16 v[48:51], v[220:223], v[188:191], v[48:51]
	v_mfma_f32_16x16x32_bf16 v[40:43], v[216:219], v[192:195], v[40:43]
	v_mfma_f32_16x16x32_bf16 v[40:43], v[220:223], v[212:215], v[40:43]
	v_mfma_f32_16x16x32_bf16 v[60:63], v[224:227], v[148:151], v[60:63]
	v_mfma_f32_16x16x32_bf16 v[60:63], v[228:231], v[152:155], v[60:63]
	v_mfma_f32_16x16x32_bf16 v[52:55], v[224:227], v[176:179], v[52:55]
	v_mfma_f32_16x16x32_bf16 v[52:55], v[228:231], v[180:183], v[52:55]
	v_mfma_f32_16x16x32_bf16 v[44:47], v[224:227], v[184:187], v[44:47]
	v_mfma_f32_16x16x32_bf16 v[44:47], v[228:231], v[188:191], v[44:47]
	v_mfma_f32_16x16x32_bf16 v[36:39], v[224:227], v[192:195], v[36:39]
	v_mfma_f32_16x16x32_bf16 v[36:39], v[228:231], v[212:215], v[36:39]
	s_setprio 0
	s_mov_b32 m0, s37
	v_lshl_add_u64 v[196:197], v[234:235], 0, s[52:53]
	s_barrier
	ds_read_b128 v[148:151], v169 offset:49152
	ds_read_b128 v[152:155], v169 offset:50176
	ds_read_b128 v[176:179], v169 offset:51200
	ds_read_b128 v[180:183], v169 offset:52224
	ds_read_b128 v[184:187], v169 offset:53248
	ds_read_b128 v[188:191], v169 offset:54272
	ds_read_b128 v[192:195], v169 offset:55296
	ds_read_b128 v[212:215], v169 offset:56320
	global_load_lds_dwordx4 v[196:197], off
	v_lshl_add_u64 v[196:197], v[236:237], 0, s[52:53]
	s_mov_b32 m0, s38
	s_nop 0
	global_load_lds_dwordx4 v[196:197], off
	s_barrier
	s_waitcnt lgkmcnt(0)
	s_setprio 1
	s_waitcnt lgkmcnt(0)
	v_mfma_f32_16x16x32_bf16 v[104:107], v[92:95], v[148:151], v[104:107]
	v_mfma_f32_16x16x32_bf16 v[104:107], v[100:103], v[152:155], v[104:107]
	v_mfma_f32_16x16x32_bf16 v[88:91], v[92:95], v[176:179], v[88:91]
	v_mfma_f32_16x16x32_bf16 v[88:91], v[100:103], v[180:183], v[88:91]
	v_mfma_f32_16x16x32_bf16 v[80:83], v[92:95], v[184:187], v[80:83]
	v_mfma_f32_16x16x32_bf16 v[80:83], v[100:103], v[188:191], v[80:83]
	v_mfma_f32_16x16x32_bf16 v[72:75], v[92:95], v[192:195], v[72:75]
	v_mfma_f32_16x16x32_bf16 v[72:75], v[100:103], v[212:215], v[72:75]
	v_mfma_f32_16x16x32_bf16 v[96:99], v[132:135], v[148:151], v[96:99]
	v_mfma_f32_16x16x32_bf16 v[96:99], v[144:147], v[152:155], v[96:99]
	v_mfma_f32_16x16x32_bf16 v[84:87], v[132:135], v[176:179], v[84:87]
	v_mfma_f32_16x16x32_bf16 v[84:87], v[144:147], v[180:183], v[84:87]
	v_mfma_f32_16x16x32_bf16 v[76:79], v[132:135], v[184:187], v[76:79]
	v_mfma_f32_16x16x32_bf16 v[76:79], v[144:147], v[188:191], v[76:79]
	v_mfma_f32_16x16x32_bf16 v[68:71], v[132:135], v[192:195], v[68:71]
	v_mfma_f32_16x16x32_bf16 v[68:71], v[144:147], v[212:215], v[68:71]
	s_setprio 0
	s_barrier
	s_add_u32 s6, s6, 0x20080
	s_addc_u32 s7, s7, 0
	s_add_i32 s10, s10, s29
	v_lshl_add_u64 v[92:93], s[6:7], 0, v[158:159]
	s_mov_b32 m0, s10
	s_nop 0
	global_load_lds_dwordx4 v[92:93], off
	v_lshl_add_u64 v[92:93], s[6:7], 0, v[0:1]
	s_add_i32 m0, s10, 0x2000
	s_nop 0
	global_load_lds_dwordx4 v[92:93], off
	s_waitcnt vmcnt(6)
	s_barrier
	s_setprio 1
	v_mfma_f32_16x16x32_bf16 v[32:35], v[216:219], v[148:151], v[32:35]
	v_mfma_f32_16x16x32_bf16 v[32:35], v[220:223], v[152:155], v[32:35]
	v_mfma_f32_16x16x32_bf16 v[24:27], v[216:219], v[176:179], v[24:27]
	v_mfma_f32_16x16x32_bf16 v[24:27], v[220:223], v[180:183], v[24:27]
	v_mfma_f32_16x16x32_bf16 v[16:19], v[216:219], v[184:187], v[16:19]
	v_mfma_f32_16x16x32_bf16 v[16:19], v[220:223], v[188:191], v[16:19]
	v_mfma_f32_16x16x32_bf16 v[8:11], v[216:219], v[192:195], v[8:11]
	v_mfma_f32_16x16x32_bf16 v[8:11], v[220:223], v[212:215], v[8:11]
	v_mfma_f32_16x16x32_bf16 v[28:31], v[224:227], v[148:151], v[28:31]
	v_mfma_f32_16x16x32_bf16 v[28:31], v[228:231], v[152:155], v[28:31]
	v_mfma_f32_16x16x32_bf16 v[20:23], v[224:227], v[176:179], v[20:23]
	v_mfma_f32_16x16x32_bf16 v[20:23], v[228:231], v[180:183], v[20:23]
	v_mfma_f32_16x16x32_bf16 v[12:15], v[224:227], v[184:187], v[12:15]
	v_mfma_f32_16x16x32_bf16 v[12:15], v[228:231], v[188:191], v[12:15]
	v_mfma_f32_16x16x32_bf16 v[4:7], v[224:227], v[192:195], v[4:7]
	v_mfma_f32_16x16x32_bf16 v[4:7], v[228:231], v[212:215], v[4:7]
	s_setprio 0
	s_add_i32 s43, s43, 2
	s_add_u32 s41, s41, 0x100
	s_addc_u32 s42, s42, 0
	s_add_u32 s4, s4, 0x100
	s_addc_u32 s5, s5, 0
	s_cmp_gt_u32 s43, 5
	s_barrier

; #define PG8_WAIT_L(n) asm volatile("s_waitcnt lgkmcnt(" #n ")" ::: "memory")
; #define PG8_BAR __builtin_amdgcn_s_barrier()
; #define PG8_SCHED __builtin_amdgcn_sched_barrier(0)
; template <class Epi, class AddrA, class AddrB>
; __device__ __forceinline__ void gemm_phase(const Sched S, const int lda, const int ldb, const int K, const AddrA addrA,
;                                            const AddrB addrB, const Epi E) {
;     ...
;     const bool has_next = S.next(ui + 1, nxt);
;     const char* nA = has_next ? addrA(nxt) : cA;
;     const char* nB = has_next ? addrB(nxt) : cB;
;     for (int t = 0; t < nt; t += 2) {
;       const bool last = (t == nt - 2);
;       const char* a1 = cA + (size_t)(t + 1) * kstep;
;       const char* a2 = last ? nA : cA + (size_t)(t + 2) * kstep;
;       const char* b2 = last ? nB : cB + (size_t)(t + 2) * kstep;
;       const char* a3 = a2 + kstep;
;       const char* b3 = b2 + kstep;
;       PG8_LDB(B0, 0, 0); PG8_SCHED; PG8_LDA(At, 0, 0); PG8_STAGE(PG8_SA(1, 1), a1 + hstepA, voffA);
;       PG8_WAIT_L(8); PG8_BAR; PG8_WAIT_L(0); PG8_MMA(0, 0, At, B0); PG8_BAR; PG8_SCHED;
;       PG8_LDB(B1, 0, 1); PG8_STAGE(PG8_SB(0, 0), b2, voffB);
;       PG8_BAR; PG8_WAIT_L(0); PG8_MMA(0, 1, At, B1); PG8_BAR;
;       PG8_LDA(At, 0, 1); PG8_STAGE(PG8_SA(0, 0), a2, voffA);
;       PG8_BAR; PG8_WAIT_L(0); PG8_MMA(1, 0, At, B0); PG8_BAR; PG8_SCHED;
.LBB0_618:
	s_ashr_i32 s3, s2, 31
	s_lshl_b64 s[8:9], s[2:3], 20
	s_add_u32 s8, s23, s8
	s_addc_u32 s9, s24, s9
	s_and_b64 s[10:11], s[18:19], exec
	s_cselect_b32 s3, s9, s17
	s_cselect_b32 s13, s8, s16
	s_ashr_i32 s5, s4, 31
	s_lshl_b64 s[10:11], s[4:5], 20
	s_add_u32 s10, s21, s10
	s_addc_u32 s11, s22, s11
	s_and_b64 s[18:19], s[18:19], exec
	s_cselect_b32 s5, s11, s15
	s_cselect_b32 s35, s10, s14
	s_add_u32 s36, s14, 0x100
	s_addc_u32 s37, s15, 0
	s_add_u32 s14, s16, 0x80080
	s_addc_u32 s15, s17, 0
	s_mov_b32 s38, -2
	s_add_u32 s16, s14, 0xfff80080
	s_addc_u32 s17, s15, -1
	s_add_i32 s39, 0, 0x10000
	v_add_u32_e32 v142, s39, v144
	ds_read_b128 v[148:151], v142
	ds_read_b128 v[152:155], v142 offset:1024
	ds_read_b128 v[156:159], v142 offset:2048
	ds_read_b128 v[160:163], v142 offset:3072
	s_cmp_eq_u32 s38, 28
	s_cselect_b32 s19, s3, s17
	s_cselect_b32 s18, s13, s16
	s_cselect_b32 s17, s5, s37
	s_cselect_b32 s16, s35, s36
	v_lshl_add_u64 v[142:143], s[14:15], 0, v[140:141]
	s_add_i32 m0, s26, 0xc000
	ds_read_b128 v[168:171], v146
	ds_read_b128 v[172:175], v146 offset:1024
	ds_read_b128 v[176:179], v146 offset:2048
	ds_read_b128 v[180:183], v146 offset:3072
	ds_read_b128 v[184:187], v146 offset:4096
	ds_read_b128 v[188:191], v146 offset:5120
	ds_read_b128 v[192:195], v146 offset:6144
	ds_read_b128 v[212:215], v146 offset:7168
	global_load_lds_dwordx4 v[142:143], off
	v_lshl_add_u64 v[142:143], s[14:15], 0, v[138:139]
	s_add_i32 m0, s26, 0xe000
	s_nop 0
	global_load_lds_dwordx4 v[142:143], off
	s_waitcnt lgkmcnt(8)
	s_barrier
	s_waitcnt lgkmcnt(0)
	s_setprio 1
	s_waitcnt lgkmcnt(0)
	v_mfma_f32_16x16x32_bf16 v[128:131], v[148:151], v[168:171], 0
	v_mfma_f32_16x16x32_bf16 v[128:131], v[152:155], v[172:175], v[128:131]
	v_mfma_f32_16x16x32_bf16 v[120:123], v[148:151], v[176:179], 0
	v_mfma_f32_16x16x32_bf16 v[120:123], v[152:155], v[180:183], v[120:123]
	v_mfma_f32_16x16x32_bf16 v[112:115], v[148:151], v[184:187], 0
	v_mfma_f32_16x16x32_bf16 v[112:115], v[152:155], v[188:191], v[112:115]
	v_mfma_f32_16x16x32_bf16 v[104:107], v[148:151], v[192:195], 0
	v_mfma_f32_16x16x32_bf16 v[104:107], v[152:155], v[212:215], v[104:107]
	v_mfma_f32_16x16x32_bf16 v[124:127], v[156:159], v[168:171], 0
	v_mfma_f32_16x16x32_bf16 v[124:127], v[160:163], v[172:175], v[124:127]
	v_mfma_f32_16x16x32_bf16 v[116:119], v[156:159], v[176:179], 0
	v_mfma_f32_16x16x32_bf16 v[116:119], v[160:163], v[180:183], v[116:119]
	v_mfma_f32_16x16x32_bf16 v[108:111], v[156:159], v[184:187], 0
	v_mfma_f32_16x16x32_bf16 v[108:111], v[160:163], v[188:191], v[108:111]
	v_mfma_f32_16x16x32_bf16 v[100:103], v[156:159], v[192:195], 0
	v_mfma_f32_16x16x32_bf16 v[100:103], v[160:163], v[212:215], v[100:103]
	s_setprio 0
	s_barrier
	s_add_i32 s42, 0, 0x14000
	v_add_u32_e32 v142, s42, v144
	s_add_i32 s39, s39, s25
	ds_read_b128 v[216:219], v142
	ds_read_b128 v[220:223], v142 offset:1024
	ds_read_b128 v[224:227], v142 offset:2048
	ds_read_b128 v[228:231], v142 offset:3072
	v_lshl_add_u64 v[142:143], s[16:17], 0, v[2:3]
	s_mov_b32 m0, s39
	v_lshl_add_u64 v[196:197], s[16:17], 0, v[0:1]
	global_load_lds_dwordx4 v[142:143], off
	s_add_i32 m0, s39, 0x2000
	s_nop 0
	global_load_lds_dwordx4 v[196:197], off
	s_barrier
	s_waitcnt lgkmcnt(0)
	s_setprio 1
	s_waitcnt lgkmcnt(0)
	v_mfma_f32_16x16x32_bf16 v[96:99], v[216:219], v[168:171], 0
	v_mfma_f32_16x16x32_bf16 v[96:99], v[220:223], v[172:175], v[96:99]
	v_mfma_f32_16x16x32_bf16 v[88:91], v[216:219], v[176:179], 0
	v_mfma_f32_16x16x32_bf16 v[88:91], v[220:223], v[180:183], v[88:91]
	v_mfma_f32_16x16x32_bf16 v[80:83], v[216:219], v[184:187], 0
	v_mfma_f32_16x16x32_bf16 v[80:83], v[220:223], v[188:191], v[80:83]
	v_mfma_f32_16x16x32_bf16 v[72:75], v[216:219], v[192:195], 0
	v_mfma_f32_16x16x32_bf16 v[72:75], v[220:223], v[212:215], v[72:75]
	v_mfma_f32_16x16x32_bf16 v[92:95], v[224:227], v[168:171], 0
	v_mfma_f32_16x16x32_bf16 v[92:95], v[228:231], v[172:175], v[92:95]
	v_mfma_f32_16x16x32_bf16 v[84:87], v[224:227], v[176:179], 0
	v_mfma_f32_16x16x32_bf16 v[84:87], v[228:231], v[180:183], v[84:87]
	v_mfma_f32_16x16x32_bf16 v[76:79], v[224:227], v[184:187], 0
	v_mfma_f32_16x16x32_bf16 v[76:79], v[228:231], v[188:191], v[76:79]
	v_mfma_f32_16x16x32_bf16 v[68:71], v[224:227], v[192:195], 0
	v_mfma_f32_16x16x32_bf16 v[68:71], v[228:231], v[212:215], v[68:71]
	s_setprio 0
	s_mov_b32 m0, s26
	v_lshl_add_u64 v[232:233], s[18:19], 0, v[134:135]
	s_barrier
	ds_read_b128 v[168:171], v146 offset:16384
	ds_read_b128 v[172:175], v146 offset:17408
	ds_read_b128 v[176:179], v146 offset:18432
	ds_read_b128 v[180:183], v146 offset:19456
	ds_read_b128 v[184:187], v146 offset:20480
	ds_read_b128 v[188:191], v146 offset:21504
	ds_read_b128 v[192:195], v146 offset:22528
	ds_read_b128 v[212:215], v146 offset:23552
	global_load_lds_dwordx4 v[232:233], off
	v_lshl_add_u64 v[234:235], s[18:19], 0, v[132:133]
	s_mov_b32 m0, s27
	s_nop 0
	global_load_lds_dwordx4 v[234:235], off
	s_barrier
	s_waitcnt lgkmcnt(0)
	s_setprio 1
	s_waitcnt lgkmcnt(0)
	v_mfma_f32_16x16x32_bf16 v[64:67], v[148:151], v[168:171], 0
	v_mfma_f32_16x16x32_bf16 v[64:67], v[152:155], v[172:175], v[64:67]
	v_mfma_f32_16x16x32_bf16 v[56:59], v[148:151], v[176:179], 0
	v_mfma_f32_16x16x32_bf16 v[56:59], v[152:155], v[180:183], v[56:59]
	v_mfma_f32_16x16x32_bf16 v[48:51], v[148:151], v[184:187], 0
	v_mfma_f32_16x16x32_bf16 v[48:51], v[152:155], v[188:191], v[48:51]
	v_mfma_f32_16x16x32_bf16 v[40:43], v[148:151], v[192:195], 0
	v_mfma_f32_16x16x32_bf16 v[40:43], v[152:155], v[212:215], v[40:43]
	v_mfma_f32_16x16x32_bf16 v[60:63], v[156:159], v[168:171], 0
	v_mfma_f32_16x16x32_bf16 v[60:63], v[160:163], v[172:175], v[60:63]
	v_mfma_f32_16x16x32_bf16 v[52:55], v[156:159], v[176:179], 0
	v_mfma_f32_16x16x32_bf16 v[52:55], v[160:163], v[180:183], v[52:55]
	v_mfma_f32_16x16x32_bf16 v[44:47], v[156:159], v[184:187], 0
	v_mfma_f32_16x16x32_bf16 v[44:47], v[160:163], v[188:191], v[44:47]
	v_mfma_f32_16x16x32_bf16 v[36:39], v[156:159], v[192:195], 0
	v_mfma_f32_16x16x32_bf16 v[36:39], v[160:163], v[212:215], v[36:39]
	s_setprio 0
	s_barrier
; #define PG8_WAIT_V(n) asm volatile("s_waitcnt vmcnt(" #n ")" ::: "memory")
; #define PG8_WAIT_L(n) asm volatile("s_waitcnt lgkmcnt(" #n ")" ::: "memory")
; #define PG8_BAR __builtin_amdgcn_s_barrier()
; #define PG8_SCHED __builtin_amdgcn_sched_barrier(0)
; template <class Epi, class AddrA, class AddrB>
; __device__ __forceinline__ void gemm_phase(const Sched S, const int lda, const int ldb, const int K, const AddrA addrA,
;                                            const AddrB addrB, const Epi E) {
;     ...
;       PG8_STAGE(PG8_SB(0, 1), b2 + hstepB, voffB);
;       PG8_WAIT_V(6); PG8_BAR; PG8_MMA(1, 1, At, B1); PG8_BAR;
;       PG8_LDB(B0, 1, 0); PG8_SCHED; PG8_LDA(At, 1, 0); PG8_STAGE(PG8_SA(0, 1), a2 + hstepA, voffA);
;       PG8_WAIT_L(8); PG8_BAR; PG8_WAIT_L(0); PG8_MMA(0, 0, At, B0); PG8_BAR; PG8_SCHED;
;       PG8_LDB(B1, 1, 1); PG8_STAGE(PG8_SB(1, 0), b3, voffB);
	s_add_u32 s40, s16, 0x80000
	s_addc_u32 s41, s17, 0
	s_add_i32 s39, s42, s25
	v_lshl_add_u64 v[148:149], s[40:41], 0, v[2:3]
	s_mov_b32 m0, s39
	s_nop 0
	global_load_lds_dwordx4 v[148:149], off
	v_lshl_add_u64 v[148:149], s[40:41], 0, v[0:1]
	s_add_i32 m0, s39, 0x2000
	s_nop 0
	global_load_lds_dwordx4 v[148:149], off
	s_waitcnt vmcnt(6)
	s_barrier
	s_setprio 1
	v_mfma_f32_16x16x32_bf16 v[32:35], v[216:219], v[168:171], 0
	v_mfma_f32_16x16x32_bf16 v[32:35], v[220:223], v[172:175], v[32:35]
	v_mfma_f32_16x16x32_bf16 v[24:27], v[216:219], v[176:179], 0
	v_mfma_f32_16x16x32_bf16 v[24:27], v[220:223], v[180:183], v[24:27]
	v_mfma_f32_16x16x32_bf16 v[16:19], v[216:219], v[184:187], 0
	v_mfma_f32_16x16x32_bf16 v[16:19], v[220:223], v[188:191], v[16:19]
	v_mfma_f32_16x16x32_bf16 v[8:11], v[216:219], v[192:195], 0
	v_mfma_f32_16x16x32_bf16 v[8:11], v[220:223], v[212:215], v[8:11]
	v_mfma_f32_16x16x32_bf16 v[28:31], v[224:227], v[168:171], 0
	v_mfma_f32_16x16x32_bf16 v[28:31], v[228:231], v[172:175], v[28:31]
	v_mfma_f32_16x16x32_bf16 v[20:23], v[224:227], v[176:179], 0
	v_mfma_f32_16x16x32_bf16 v[20:23], v[228:231], v[180:183], v[20:23]
	v_mfma_f32_16x16x32_bf16 v[12:15], v[224:227], v[184:187], 0
	v_mfma_f32_16x16x32_bf16 v[12:15], v[228:231], v[188:191], v[12:15]
	v_mfma_f32_16x16x32_bf16 v[4:7], v[224:227], v[192:195], 0
	v_mfma_f32_16x16x32_bf16 v[4:7], v[228:231], v[212:215], v[4:7]
	s_setprio 0
	s_add_i32 s39, 0, 0x18000
	v_add_u32_e32 v147, s39, v144
	s_barrier
	ds_read_b128 v[148:151], v147
	ds_read_b128 v[152:155], v147 offset:1024
	ds_read_b128 v[156:159], v147 offset:2048
	ds_read_b128 v[160:163], v147 offset:3072
	s_add_u32 s18, s18, 0x80000
	s_addc_u32 s19, s19, 0
	s_mov_b32 m0, s28
	v_lshl_add_u64 v[216:217], s[18:19], 0, v[134:135]
	ds_read_b128 v[168:171], v146 offset:32768
	ds_read_b128 v[172:175], v146 offset:33792
	ds_read_b128 v[176:179], v146 offset:34816
	ds_read_b128 v[180:183], v146 offset:35840
	ds_read_b128 v[184:187], v146 offset:36864
	ds_read_b128 v[188:191], v146 offset:37888
	ds_read_b128 v[192:195], v146 offset:38912
	ds_read_b128 v[212:215], v146 offset:39936
	global_load_lds_dwordx4 v[216:217], off
	v_lshl_add_u64 v[216:217], s[18:19], 0, v[132:133]
	s_mov_b32 m0, s29
	s_nop 0
	global_load_lds_dwordx4 v[216:217], off
	s_waitcnt lgkmcnt(8)
	s_barrier
	s_waitcnt lgkmcnt(0)
	s_setprio 1
	s_waitcnt lgkmcnt(0)
	v_mfma_f32_16x16x32_bf16 v[128:131], v[148:151], v[168:171], v[128:131]
	v_mfma_f32_16x16x32_bf16 v[128:131], v[152:155], v[172:175], v[128:131]
	v_mfma_f32_16x16x32_bf16 v[120:123], v[148:151], v[176:179], v[120:123]
	v_mfma_f32_16x16x32_bf16 v[120:123], v[152:155], v[180:183], v[120:123]
	v_mfma_f32_16x16x32_bf16 v[112:115], v[148:151], v[184:187], v[112:115]
	v_mfma_f32_16x16x32_bf16 v[112:115], v[152:155], v[188:191], v[112:115]
	v_mfma_f32_16x16x32_bf16 v[104:107], v[148:151], v[192:195], v[104:107]
	v_mfma_f32_16x16x32_bf16 v[104:107], v[152:155], v[212:215], v[104:107]
	v_mfma_f32_16x16x32_bf16 v[124:127], v[156:159], v[168:171], v[124:127]
	v_mfma_f32_16x16x32_bf16 v[124:127], v[160:163], v[172:175], v[124:127]
	v_mfma_f32_16x16x32_bf16 v[116:119], v[156:159], v[176:179], v[116:119]
	v_mfma_f32_16x16x32_bf16 v[116:119], v[160:163], v[180:183], v[116:119]
	v_mfma_f32_16x16x32_bf16 v[108:111], v[156:159], v[184:187], v[108:111]
	v_mfma_f32_16x16x32_bf16 v[108:111], v[160:163], v[188:191], v[108:111]
	v_mfma_f32_16x16x32_bf16 v[100:103], v[156:159], v[192:195], v[100:103]
	v_mfma_f32_16x16x32_bf16 v[100:103], v[160:163], v[212:215], v[100:103]
	s_setprio 0
	s_barrier
	s_add_i32 s18, 0, 0x1c000
	s_add_i32 s19, s39, s25
	v_add_u32_e32 v147, s18, v144
	v_lshl_add_u64 v[142:143], v[142:143], 0, s[52:53]
	s_mov_b32 m0, s19
	ds_read_b128 v[216:219], v147
	ds_read_b128 v[220:223], v147 offset:1024
	ds_read_b128 v[224:227], v147 offset:2048
	ds_read_b128 v[228:231], v147 offset:3072
	global_load_lds_dwordx4 v[142:143], off
	v_lshl_add_u64 v[142:143], v[196:197], 0, s[52:53]
	s_add_i32 m0, s19, 0x2000
	s_nop 0
	global_load_lds_dwordx4 v[142:143], off
	s_barrier
; #define PG8_WAIT_V(n) asm volatile("s_waitcnt vmcnt(" #n ")" ::: "memory")
; #define PG8_WAIT_L(n) asm volatile("s_waitcnt lgkmcnt(" #n ")" ::: "memory")
; #define PG8_BAR __builtin_amdgcn_s_barrier()
; #define PG8_SCHED __builtin_amdgcn_sched_barrier(0)
; template <class Epi, class AddrA, class AddrB>
; __device__ __forceinline__ void gemm_phase(const Sched S, const int lda, const int ldb, const int K, const AddrA addrA,
;                                            const AddrB addrB, const Epi E) {
;     ...
;       PG8_BAR; PG8_WAIT_L(0); PG8_MMA(0, 1, At, B1); PG8_BAR;
;       PG8_LDA(At, 1, 1); PG8_STAGE(PG8_SA(1, 0), a3, voffA);
;       PG8_BAR; PG8_WAIT_L(0); PG8_MMA(1, 0, At, B0); PG8_BAR; PG8_SCHED;
;       PG8_STAGE(PG8_SB(1, 1), b3 + hstepB, voffB);
;       PG8_WAIT_V(6); PG8_BAR; PG8_MMA(1, 1, At, B1); PG8_BAR;
	s_waitcnt lgkmcnt(0)
	s_setprio 1
	s_waitcnt lgkmcnt(0)
	v_mfma_f32_16x16x32_bf16 v[96:99], v[216:219], v[168:171], v[96:99]
	v_mfma_f32_16x16x32_bf16 v[96:99], v[220:223], v[172:175], v[96:99]
	v_mfma_f32_16x16x32_bf16 v[88:91], v[216:219], v[176:179], v[88:91]
	v_mfma_f32_16x16x32_bf16 v[88:91], v[220:223], v[180:183], v[88:91]
	v_mfma_f32_16x16x32_bf16 v[80:83], v[216:219], v[184:187], v[80:83]
	v_mfma_f32_16x16x32_bf16 v[80:83], v[220:223], v[188:191], v[80:83]
	v_mfma_f32_16x16x32_bf16 v[72:75], v[216:219], v[192:195], v[72:75]
	v_mfma_f32_16x16x32_bf16 v[72:75], v[220:223], v[212:215], v[72:75]
	v_mfma_f32_16x16x32_bf16 v[92:95], v[224:227], v[168:171], v[92:95]
	v_mfma_f32_16x16x32_bf16 v[92:95], v[228:231], v[172:175], v[92:95]
	v_mfma_f32_16x16x32_bf16 v[84:87], v[224:227], v[176:179], v[84:87]
	v_mfma_f32_16x16x32_bf16 v[84:87], v[228:231], v[180:183], v[84:87]
	v_mfma_f32_16x16x32_bf16 v[76:79], v[224:227], v[184:187], v[76:79]
	v_mfma_f32_16x16x32_bf16 v[76:79], v[228:231], v[188:191], v[76:79]
	v_mfma_f32_16x16x32_bf16 v[68:71], v[224:227], v[192:195], v[68:71]
	v_mfma_f32_16x16x32_bf16 v[68:71], v[228:231], v[212:215], v[68:71]
	s_setprio 0
	s_mov_b32 m0, s30
	v_lshl_add_u64 v[142:143], v[232:233], 0, s[52:53]
	s_barrier
	ds_read_b128 v[168:171], v146 offset:49152
	ds_read_b128 v[172:175], v146 offset:50176
	ds_read_b128 v[176:179], v146 offset:51200
	ds_read_b128 v[180:183], v146 offset:52224
	ds_read_b128 v[184:187], v146 offset:53248
	ds_read_b128 v[188:191], v146 offset:54272
	ds_read_b128 v[192:195], v146 offset:55296
	ds_read_b128 v[212:215], v146 offset:56320
	global_load_lds_dwordx4 v[142:143], off
	v_lshl_add_u64 v[142:143], v[234:235], 0, s[52:53]
	s_mov_b32 m0, s31
	s_nop 0
	global_load_lds_dwordx4 v[142:143], off
	s_barrier
	s_waitcnt lgkmcnt(0)
	s_setprio 1
	s_waitcnt lgkmcnt(0)
	v_mfma_f32_16x16x32_bf16 v[64:67], v[148:151], v[168:171], v[64:67]
	v_mfma_f32_16x16x32_bf16 v[64:67], v[152:155], v[172:175], v[64:67]
	v_mfma_f32_16x16x32_bf16 v[56:59], v[148:151], v[176:179], v[56:59]
	v_mfma_f32_16x16x32_bf16 v[56:59], v[152:155], v[180:183], v[56:59]
	v_mfma_f32_16x16x32_bf16 v[48:51], v[148:151], v[184:187], v[48:51]
	v_mfma_f32_16x16x32_bf16 v[48:51], v[152:155], v[188:191], v[48:51]
	v_mfma_f32_16x16x32_bf16 v[40:43], v[148:151], v[192:195], v[40:43]
	v_mfma_f32_16x16x32_bf16 v[40:43], v[152:155], v[212:215], v[40:43]
	v_mfma_f32_16x16x32_bf16 v[60:63], v[156:159], v[168:171], v[60:63]
	v_mfma_f32_16x16x32_bf16 v[60:63], v[160:163], v[172:175], v[60:63]
	v_mfma_f32_16x16x32_bf16 v[52:55], v[156:159], v[176:179], v[52:55]
	v_mfma_f32_16x16x32_bf16 v[52:55], v[160:163], v[180:183], v[52:55]
	v_mfma_f32_16x16x32_bf16 v[44:47], v[156:159], v[184:187], v[44:47]
	v_mfma_f32_16x16x32_bf16 v[44:47], v[160:163], v[188:191], v[44:47]
	v_mfma_f32_16x16x32_bf16 v[36:39], v[156:159], v[192:195], v[36:39]
	v_mfma_f32_16x16x32_bf16 v[36:39], v[160:163], v[212:215], v[36:39]
	s_setprio 0
	s_barrier
	s_add_u32 s16, s16, 0x80080
	s_addc_u32 s17, s17, 0
	s_add_i32 s18, s18, s25
	v_lshl_add_u64 v[142:143], s[16:17], 0, v[2:3]
	s_mov_b32 m0, s18
	s_nop 0
	global_load_lds_dwordx4 v[142:143], off
	v_lshl_add_u64 v[142:143], s[16:17], 0, v[0:1]
	s_add_i32 m0, s18, 0x2000
	s_nop 0
	global_load_lds_dwordx4 v[142:143], off
	s_waitcnt vmcnt(6)
	s_barrier
	s_setprio 1
	v_mfma_f32_16x16x32_bf16 v[32:35], v[216:219], v[168:171], v[32:35]
	v_mfma_f32_16x16x32_bf16 v[32:35], v[220:223], v[172:175], v[32:35]
	v_mfma_f32_16x16x32_bf16 v[24:27], v[216:219], v[176:179], v[24:27]
	v_mfma_f32_16x16x32_bf16 v[24:27], v[220:223], v[180:183], v[24:27]
	v_mfma_f32_16x16x32_bf16 v[16:19], v[216:219], v[184:187], v[16:19]
	v_mfma_f32_16x16x32_bf16 v[16:19], v[220:223], v[188:191], v[16:19]
	v_mfma_f32_16x16x32_bf16 v[8:11], v[216:219], v[192:195], v[8:11]
	v_mfma_f32_16x16x32_bf16 v[8:11], v[220:223], v[212:215], v[8:11]
	v_mfma_f32_16x16x32_bf16 v[28:31], v[224:227], v[168:171], v[28:31]
	v_mfma_f32_16x16x32_bf16 v[28:31], v[228:231], v[172:175], v[28:31]
	v_mfma_f32_16x16x32_bf16 v[20:23], v[224:227], v[176:179], v[20:23]
	v_mfma_f32_16x16x32_bf16 v[20:23], v[228:231], v[180:183], v[20:23]
	v_mfma_f32_16x16x32_bf16 v[12:15], v[224:227], v[184:187], v[12:15]
	v_mfma_f32_16x16x32_bf16 v[12:15], v[228:231], v[188:191], v[12:15]
	v_mfma_f32_16x16x32_bf16 v[4:7], v[224:227], v[192:195], v[4:7]
	v_mfma_f32_16x16x32_bf16 v[4:7], v[228:231], v[212:215], v[4:7]
	s_setprio 0
	s_add_i32 s38, s38, 2
	s_add_u32 s36, s36, 0x100
	s_addc_u32 s37, s37, 0
	s_add_u32 s14, s14, 0x100
	s_addc_u32 s15, s15, 0
	s_cmp_gt_u32 s38, 29
	s_barrier
